# FFN-up epilogue: all four per-block ss loads issued in the first row block (later blocks no longer drain stores with vmcnt(0)); on top of attention store widening
# speedup vs baseline: 1.0449x; 1.0058x over previous
; __device__ __forceinline__ int ltid() { int t = threadIdx.x; asm volatile("" : "+v"(t)); return t; }
; __device__ __forceinline__ float sigm(float x) { return __builtin_amdgcn_rcpf(1.f + __builtin_amdgcn_exp2f(-LOG2E * x)); }
; __device__ __forceinline__ void epi_swiglu(const f32x16 (&acc)[2][2], int nbase, int tbase, int M, const float* ss, u16* ACT) {
;   const int lane = ltid() & 63, l32 = lane & 31, h = lane >> 5;
;   const int cb = (nbase >> 6) * 32;
; #pragma unroll
;   for (int tb = 0; tb < 2; ++tb) {
;     const int tok = tbase + tb * 32 + l32;
;     if (tok < M) {
;       const float rs = rsqrtf(ss[tok] * (1.f / 1024.f) + EPSN);
;       u16* dst = ACT + (size_t)tok * FFD + cb + 4 * h;
; #pragma unroll
;       for (int i = 0; i < 4; ++i) {
;         float o[4];
; #pragma unroll
;         for (int j = 0; j < 4; ++j) {
;           const float g = acc[0][tb][4 * i + j] * rs, u = acc[1][tb][4 * i + j] * rs;
;           o[j] = g * sigm(g) * u;
;         }
;         *(u32x2*)(dst + 8 * i) = (u32x2){pk_bf16(o[0], o[1]), pk_bf16(o[2], o[3])};
;       }
;     }
;   }
; }
.LBB0_93:
	s_or_b64 exec, exec, s[6:7]
	v_mov_b32_e32 v146, v204
	s_load_dwordx2 s[0:1], s[64:65], 0x1c8
	v_lshl_or_b32 v144, v170, 7, v168
	v_lshl_add_u32 v155, v160, 8, v169
	v_ashrrev_i32_e32 v144, 1, v144
	v_and_or_b32 v148, v146, 31, v155
	v_ashrrev_i32_e32 v145, 31, v144
	v_lshrrev_b32_e32 v146, 2, v146
	s_waitcnt lgkmcnt(0)
	v_lshl_add_u64 v[144:145], v[144:145], 1, s[0:1]
	v_and_b32_e32 v160, 8, v146
	v_lshl_add_u64 v[146:147], v[144:145], 0, v[160:161]
	v_cmp_gt_i32_e64 s[40:41], s62, v148
	v_ashrrev_i32_e32 v149, 31, v148
	s_and_saveexec_b64 s[34:35], s[40:41]
	s_cbranch_execz .LBB0_95
	v_lshl_add_u64 v[150:151], v[148:149], 2, s[44:45]
	global_load_dword v243, v[150:151], off offset:128
	global_load_dword v244, v[150:151], off offset:512
	global_load_dword v245, v[150:151], off offset:640
	global_load_dword v150, v[150:151], off
	s_waitcnt vmcnt(0)
	v_fmamk_f32 v150, v150, 0x3a800000, v205
	v_cmp_gt_f32_e64 s[40:41], s21, v150
	v_mul_f32_e32 v151, 0x4b800000, v150
	s_nop 0
	v_cndmask_b32_e64 v150, v150, v151, s[40:41]
	v_rsq_f32_e32 v150, v150
	s_nop 0
	v_mul_f32_e32 v151, 0x45800000, v150
	v_cndmask_b32_e64 v152, v150, v151, s[40:41]
	v_pk_mul_f32 v[112:113], v[112:113], v[152:153] op_sel_hi:[1,0]
	v_pk_mul_f32 v[96:97], v[96:97], v[152:153] op_sel_hi:[1,0]
	v_mul_f32_e32 v160, 0xbfb8aa3b, v112
	v_exp_f32_e32 v160, v160
	v_pk_mul_f32 v[98:99], v[98:99], v[152:153] op_sel_hi:[1,0]
	v_mad_i64_i32 v[150:151], s[0:1], v148, s56, v[146:147]
	v_add_f32_e32 v160, 1.0, v160
	v_rcp_f32_e32 v170, v160
	v_mul_f32_e32 v160, 0xbfb8aa3b, v113
	v_exp_f32_e32 v160, v160
	v_pk_mul_f32 v[100:101], v[100:101], v[152:153] op_sel_hi:[1,0]
	v_pk_mul_f32 v[102:103], v[102:103], v[152:153] op_sel_hi:[1,0]
	v_add_f32_e32 v160, 1.0, v160
	v_rcp_f32_e32 v171, v160
	s_nop 0
	v_pk_mul_f32 v[112:113], v[112:113], v[170:171]
	s_nop 0
	v_pk_mul_f32 v[96:97], v[96:97], v[112:113]
	v_pk_mul_f32 v[112:113], v[114:115], v[152:153] op_sel_hi:[1,0]
	v_cvt_pk_bf16_f32 v96, v96, v97
	v_mul_f32_e32 v114, 0xbfb8aa3b, v112
	v_mul_f32_e32 v115, 0xbfb8aa3b, v113
	v_exp_f32_e32 v114, v114
	v_exp_f32_e32 v115, v115
	v_add_f32_e32 v114, 1.0, v114
	v_add_f32_e32 v115, 1.0, v115
	v_rcp_f32_e32 v114, v114
	v_rcp_f32_e32 v115, v115
	s_nop 0
	v_pk_mul_f32 v[112:113], v[112:113], v[114:115]
	s_nop 0
	v_pk_mul_f32 v[98:99], v[98:99], v[112:113]
	s_nop 0
	v_cvt_pk_bf16_f32 v97, v98, v99
	v_mov_b32_e32 v222, v96
	v_mov_b32_e32 v223, v97
	v_pk_mul_f32 v[96:97], v[116:117], v[152:153] op_sel_hi:[1,0]
	s_nop 0
	v_mul_f32_e32 v98, 0xbfb8aa3b, v96
	v_mul_f32_e32 v99, 0xbfb8aa3b, v97
	v_exp_f32_e32 v98, v98
	v_exp_f32_e32 v99, v99
	v_add_f32_e32 v98, 1.0, v98
	v_add_f32_e32 v99, 1.0, v99
	v_rcp_f32_e32 v98, v98
	v_rcp_f32_e32 v99, v99
	s_nop 0
	v_pk_mul_f32 v[96:97], v[96:97], v[98:99]
	v_pk_mul_f32 v[98:99], v[118:119], v[152:153] op_sel_hi:[1,0]
	v_pk_mul_f32 v[96:97], v[100:101], v[96:97]
	v_mul_f32_e32 v100, 0xbfb8aa3b, v98
	v_mul_f32_e32 v101, 0xbfb8aa3b, v99
	v_exp_f32_e32 v100, v100
	v_exp_f32_e32 v101, v101
	v_cvt_pk_bf16_f32 v96, v96, v97
	v_add_f32_e32 v100, 1.0, v100
	v_add_f32_e32 v101, 1.0, v101
	v_rcp_f32_e32 v100, v100
	v_rcp_f32_e32 v101, v101
	s_nop 0
	v_pk_mul_f32 v[98:99], v[98:99], v[100:101]
	s_nop 0
	v_pk_mul_f32 v[98:99], v[102:103], v[98:99]
	v_pk_mul_f32 v[100:101], v[104:105], v[152:153] op_sel_hi:[1,0]
	v_cvt_pk_bf16_f32 v97, v98, v99
	v_mov_b32_e32 v224, v96
	v_mov_b32_e32 v225, v97
	v_lshrrev_b32_e32 v238, 2, v204
	v_and_b32_e32 v238, 8, v238
	v_mov_b32_e32 v239, 0
	v_lshl_add_u64 v[240:241], v[150:151], 0, v[238:239]
	v_permlane32_swap_b32_e32 v222, v224
	v_permlane32_swap_b32_e32 v223, v225
	global_store_dwordx4 v[240:241], v[222:225], off
	v_pk_mul_f32 v[96:97], v[120:121], v[152:153] op_sel_hi:[1,0]
	v_pk_mul_f32 v[102:103], v[106:107], v[152:153] op_sel_hi:[1,0]
	v_mul_f32_e32 v98, 0xbfb8aa3b, v96
	v_mul_f32_e32 v99, 0xbfb8aa3b, v97
	v_exp_f32_e32 v98, v98
	v_exp_f32_e32 v99, v99
	v_add_f32_e32 v98, 1.0, v98
	v_add_f32_e32 v99, 1.0, v99
	v_rcp_f32_e32 v98, v98
	v_rcp_f32_e32 v99, v99
	s_nop 0
	v_pk_mul_f32 v[96:97], v[96:97], v[98:99]
	v_pk_mul_f32 v[98:99], v[122:123], v[152:153] op_sel_hi:[1,0]
	v_pk_mul_f32 v[96:97], v[100:101], v[96:97]
	v_mul_f32_e32 v100, 0xbfb8aa3b, v98
	v_mul_f32_e32 v101, 0xbfb8aa3b, v99
	v_exp_f32_e32 v100, v100
	v_exp_f32_e32 v101, v101
	v_cvt_pk_bf16_f32 v96, v96, v97
	v_add_f32_e32 v100, 1.0, v100
	v_add_f32_e32 v101, 1.0, v101
	v_rcp_f32_e32 v100, v100
	v_rcp_f32_e32 v101, v101
	s_nop 0
	v_pk_mul_f32 v[98:99], v[98:99], v[100:101]
	s_nop 0
	v_pk_mul_f32 v[98:99], v[102:103], v[98:99]
	v_pk_mul_f32 v[100:101], v[108:109], v[152:153] op_sel_hi:[1,0]
	v_cvt_pk_bf16_f32 v97, v98, v99
	v_mov_b32_e32 v226, v96
	v_mov_b32_e32 v227, v97
	v_pk_mul_f32 v[96:97], v[124:125], v[152:153] op_sel_hi:[1,0]
	v_pk_mul_f32 v[102:103], v[110:111], v[152:153] op_sel_hi:[1,0]
	v_mul_f32_e32 v98, 0xbfb8aa3b, v96
	v_mul_f32_e32 v99, 0xbfb8aa3b, v97
	v_exp_f32_e32 v98, v98
	v_exp_f32_e32 v99, v99
	v_add_f32_e32 v98, 1.0, v98
	v_add_f32_e32 v99, 1.0, v99
	v_rcp_f32_e32 v98, v98
	v_rcp_f32_e32 v99, v99
	s_nop 0
	v_pk_mul_f32 v[96:97], v[96:97], v[98:99]
	v_pk_mul_f32 v[98:99], v[126:127], v[152:153] op_sel_hi:[1,0]
	v_pk_mul_f32 v[96:97], v[100:101], v[96:97]
	v_mul_f32_e32 v100, 0xbfb8aa3b, v98
	v_mul_f32_e32 v101, 0xbfb8aa3b, v99
	v_exp_f32_e32 v100, v100
	v_exp_f32_e32 v101, v101
	v_cvt_pk_bf16_f32 v96, v96, v97
	v_add_f32_e32 v100, 1.0, v100
	v_add_f32_e32 v101, 1.0, v101
	v_rcp_f32_e32 v100, v100
	v_rcp_f32_e32 v101, v101
	s_nop 0
	v_pk_mul_f32 v[98:99], v[98:99], v[100:101]
	s_nop 0
	v_pk_mul_f32 v[98:99], v[102:103], v[98:99]
	s_nop 0
	v_cvt_pk_bf16_f32 v97, v98, v99
	v_mov_b32_e32 v228, v96
	v_mov_b32_e32 v229, v97
	s_nop 1
	v_permlane32_swap_b32_e32 v226, v228
	v_permlane32_swap_b32_e32 v227, v229
	global_store_dwordx4 v[240:241], v[226:229], off offset:32
; __device__ __forceinline__ float sigm(float x) { return __builtin_amdgcn_rcpf(1.f + __builtin_amdgcn_exp2f(-LOG2E * x)); }
; __device__ __forceinline__ void epi_swiglu(const f32x16 (&acc)[2][2], int nbase, int tbase, int M, const float* ss, u16* ACT) {
;     ...
;     const int tok = tbase + tb * 32 + l32;
;     if (tok < M) {
;       const float rs = rsqrtf(ss[tok] * (1.f / 1024.f) + EPSN);
;       u16* dst = ACT + (size_t)tok * FFD + cb + 4 * h;
; #pragma unroll
;       for (int i = 0; i < 4; ++i) {
;         float o[4];
; #pragma unroll
;         for (int j = 0; j < 4; ++j) {
;           const float g = acc[0][tb][4 * i + j] * rs, u = acc[1][tb][4 * i + j] * rs;
;           o[j] = g * sigm(g) * u;
;         }
;         *(u32x2*)(dst + 8 * i) = (u32x2){pk_bf16(o[0], o[1]), pk_bf16(o[2], o[3])};
;       }
.LBB0_95:
	s_or_b64 exec, exec, s[34:35]
	v_or_b32_e32 v96, 32, v148
	v_cmp_gt_i32_e64 s[40:41], s62, v96
	s_and_saveexec_b64 s[34:35], s[40:41]
	s_cbranch_execz .LBB0_97
	v_lshl_add_u64 v[98:99], v[148:149], 2, s[44:45]
	v_mov_b32_e32 v97, v243
	v_fmamk_f32 v97, v97, 0x3a800000, v205
	v_cmp_gt_f32_e64 s[40:41], s21, v97
	v_mul_f32_e32 v98, 0x4b800000, v97
	s_nop 0
	v_cndmask_b32_e64 v97, v97, v98, s[40:41]
	v_rsq_f32_e32 v97, v97
	s_nop 0
	v_mul_f32_e32 v98, 0x45800000, v97
	v_cndmask_b32_e64 v98, v97, v98, s[40:41]
	v_pk_mul_f32 v[80:81], v[80:81], v[98:99] op_sel_hi:[1,0]
	v_mad_i64_i32 v[96:97], s[0:1], v96, s56, v[146:147]
	v_mul_f32_e32 v99, 0xbfb8aa3b, v80
	v_exp_f32_e32 v99, v99
	s_nop 0
	v_add_f32_e32 v99, 1.0, v99
	v_rcp_f32_e32 v100, v99
	v_pk_mul_f32 v[64:65], v[64:65], v[98:99] op_sel_hi:[1,0]
	v_mul_f32_e32 v99, 0xbfb8aa3b, v81
	v_exp_f32_e32 v99, v99
	s_nop 0
	v_add_f32_e32 v99, 1.0, v99
	v_rcp_f32_e32 v101, v99
	v_pk_mul_f32 v[66:67], v[66:67], v[98:99] op_sel_hi:[1,0]
	v_pk_mul_f32 v[68:69], v[68:69], v[98:99] op_sel_hi:[1,0]
	v_pk_mul_f32 v[70:71], v[70:71], v[98:99] op_sel_hi:[1,0]
	v_pk_mul_f32 v[80:81], v[80:81], v[100:101]
	s_nop 0
	v_pk_mul_f32 v[64:65], v[64:65], v[80:81]
	v_pk_mul_f32 v[80:81], v[82:83], v[98:99] op_sel_hi:[1,0]
	v_cvt_pk_bf16_f32 v64, v64, v65
	v_mul_f32_e32 v82, 0xbfb8aa3b, v80
	v_mul_f32_e32 v83, 0xbfb8aa3b, v81
	v_exp_f32_e32 v82, v82
	v_exp_f32_e32 v83, v83
	v_add_f32_e32 v82, 1.0, v82
	v_add_f32_e32 v83, 1.0, v83
	v_rcp_f32_e32 v82, v82
	v_rcp_f32_e32 v83, v83
	s_nop 0
	v_pk_mul_f32 v[80:81], v[80:81], v[82:83]
	s_nop 0
	v_pk_mul_f32 v[66:67], v[66:67], v[80:81]
	s_nop 0
	v_cvt_pk_bf16_f32 v65, v66, v67
	v_mov_b32_e32 v230, v64
	v_mov_b32_e32 v231, v65
	v_pk_mul_f32 v[64:65], v[84:85], v[98:99] op_sel_hi:[1,0]
	s_nop 0
	v_mul_f32_e32 v66, 0xbfb8aa3b, v64
	v_mul_f32_e32 v67, 0xbfb8aa3b, v65
	v_exp_f32_e32 v66, v66
	v_exp_f32_e32 v67, v67
	v_add_f32_e32 v66, 1.0, v66
	v_add_f32_e32 v67, 1.0, v67
	v_rcp_f32_e32 v66, v66
	v_rcp_f32_e32 v67, v67
	s_nop 0
	v_pk_mul_f32 v[64:65], v[64:65], v[66:67]
	v_pk_mul_f32 v[66:67], v[86:87], v[98:99] op_sel_hi:[1,0]
	v_pk_mul_f32 v[64:65], v[68:69], v[64:65]
	v_mul_f32_e32 v68, 0xbfb8aa3b, v66
	v_mul_f32_e32 v69, 0xbfb8aa3b, v67
	v_exp_f32_e32 v68, v68
	v_exp_f32_e32 v69, v69
	v_cvt_pk_bf16_f32 v64, v64, v65
	v_add_f32_e32 v68, 1.0, v68
	v_add_f32_e32 v69, 1.0, v69
	v_rcp_f32_e32 v68, v68
	v_rcp_f32_e32 v69, v69
	s_nop 0
	v_pk_mul_f32 v[66:67], v[66:67], v[68:69]
	s_nop 0
	v_pk_mul_f32 v[66:67], v[70:71], v[66:67]
	v_pk_mul_f32 v[68:69], v[72:73], v[98:99] op_sel_hi:[1,0]
	v_cvt_pk_bf16_f32 v65, v66, v67
	v_mov_b32_e32 v232, v64
	v_mov_b32_e32 v233, v65
	v_lshrrev_b32_e32 v238, 2, v204
	v_and_b32_e32 v238, 8, v238
	v_mov_b32_e32 v239, 0
	v_lshl_add_u64 v[240:241], v[96:97], 0, v[238:239]
	v_permlane32_swap_b32_e32 v230, v232
	v_permlane32_swap_b32_e32 v231, v233
	global_store_dwordx4 v[240:241], v[230:233], off
	v_pk_mul_f32 v[64:65], v[88:89], v[98:99] op_sel_hi:[1,0]
	v_pk_mul_f32 v[70:71], v[74:75], v[98:99] op_sel_hi:[1,0]
	v_mul_f32_e32 v66, 0xbfb8aa3b, v64
	v_mul_f32_e32 v67, 0xbfb8aa3b, v65
	v_exp_f32_e32 v66, v66
	v_exp_f32_e32 v67, v67
	v_add_f32_e32 v66, 1.0, v66
	v_add_f32_e32 v67, 1.0, v67
	v_rcp_f32_e32 v66, v66
	v_rcp_f32_e32 v67, v67
	s_nop 0
	v_pk_mul_f32 v[64:65], v[64:65], v[66:67]
	v_pk_mul_f32 v[66:67], v[90:91], v[98:99] op_sel_hi:[1,0]
	v_pk_mul_f32 v[64:65], v[68:69], v[64:65]
	v_mul_f32_e32 v68, 0xbfb8aa3b, v66
	v_mul_f32_e32 v69, 0xbfb8aa3b, v67
	v_exp_f32_e32 v68, v68
	v_exp_f32_e32 v69, v69
	v_cvt_pk_bf16_f32 v64, v64, v65
	v_add_f32_e32 v68, 1.0, v68
	v_add_f32_e32 v69, 1.0, v69
	v_rcp_f32_e32 v68, v68
	v_rcp_f32_e32 v69, v69
	s_nop 0
	v_pk_mul_f32 v[66:67], v[66:67], v[68:69]
	s_nop 0
	v_pk_mul_f32 v[66:67], v[70:71], v[66:67]
	v_pk_mul_f32 v[68:69], v[76:77], v[98:99] op_sel_hi:[1,0]
	v_cvt_pk_bf16_f32 v65, v66, v67
	v_mov_b32_e32 v234, v64
	v_mov_b32_e32 v235, v65
	v_pk_mul_f32 v[64:65], v[92:93], v[98:99] op_sel_hi:[1,0]
	v_pk_mul_f32 v[70:71], v[78:79], v[98:99] op_sel_hi:[1,0]
	v_mul_f32_e32 v66, 0xbfb8aa3b, v64
	v_mul_f32_e32 v67, 0xbfb8aa3b, v65
	v_exp_f32_e32 v66, v66
	v_exp_f32_e32 v67, v67
	v_add_f32_e32 v66, 1.0, v66
	v_add_f32_e32 v67, 1.0, v67
	v_rcp_f32_e32 v66, v66
	v_rcp_f32_e32 v67, v67
	s_nop 0
	v_pk_mul_f32 v[64:65], v[64:65], v[66:67]
	v_pk_mul_f32 v[66:67], v[94:95], v[98:99] op_sel_hi:[1,0]
	v_pk_mul_f32 v[64:65], v[68:69], v[64:65]
	v_mul_f32_e32 v68, 0xbfb8aa3b, v66
	v_mul_f32_e32 v69, 0xbfb8aa3b, v67
	v_exp_f32_e32 v68, v68
	v_exp_f32_e32 v69, v69
	v_cvt_pk_bf16_f32 v64, v64, v65
	v_add_f32_e32 v68, 1.0, v68
	v_add_f32_e32 v69, 1.0, v69
	v_rcp_f32_e32 v68, v68
	v_rcp_f32_e32 v69, v69
	s_nop 0
	v_pk_mul_f32 v[66:67], v[66:67], v[68:69]
	s_nop 0
	v_pk_mul_f32 v[66:67], v[70:71], v[66:67]
	s_nop 0
	v_cvt_pk_bf16_f32 v65, v66, v67
	v_mov_b32_e32 v236, v64
	v_mov_b32_e32 v237, v65
	s_nop 1
	v_permlane32_swap_b32_e32 v234, v236
	v_permlane32_swap_b32_e32 v235, v237
	global_store_dwordx4 v[240:241], v[234:237], off offset:32
; __device__ __forceinline__ float sigm(float x) { return __builtin_amdgcn_rcpf(1.f + __builtin_amdgcn_exp2f(-LOG2E * x)); }
; __device__ __forceinline__ void epi_swiglu(const f32x16 (&acc)[2][2], int nbase, int tbase, int M, const float* ss, u16* ACT) {
;     ...
;     const int tok = tbase + tb * 32 + l32;
;     if (tok < M) {
;       const float rs = rsqrtf(ss[tok] * (1.f / 1024.f) + EPSN);
;       u16* dst = ACT + (size_t)tok * FFD + cb + 4 * h;
; #pragma unroll
;       for (int i = 0; i < 4; ++i) {
;         float o[4];
; #pragma unroll
;         for (int j = 0; j < 4; ++j) {
;           const float g = acc[0][tb][4 * i + j] * rs, u = acc[1][tb][4 * i + j] * rs;
;           o[j] = g * sigm(g) * u;
;         }
;         *(u32x2*)(dst + 8 * i) = (u32x2){pk_bf16(o[0], o[1]), pk_bf16(o[2], o[3])};
;       }
.LBB0_97:
	s_or_b64 exec, exec, s[34:35]
	v_mov_b32_e32 v64, v204
	s_movk_i32 s0, 0x80
	v_and_b32_e32 v65, 31, v64
	v_lshrrev_b32_e32 v64, 2, v64
	v_add3_u32 v66, v155, v65, s0
	v_and_b32_e32 v160, 8, v64
	v_lshl_add_u64 v[64:65], v[144:145], 0, v[160:161]
	v_cmp_gt_i32_e64 s[40:41], s62, v66
	v_ashrrev_i32_e32 v67, 31, v66
	s_and_saveexec_b64 s[34:35], s[40:41]
	s_cbranch_execz .LBB0_99
	v_lshl_add_u64 v[68:69], v[66:67], 2, s[44:45]
	v_mov_b32_e32 v68, v244
	v_fmamk_f32 v68, v68, 0x3a800000, v205
	v_cmp_gt_f32_e64 s[40:41], s21, v68
	v_mul_f32_e32 v69, 0x4b800000, v68
	s_nop 0
	v_cndmask_b32_e64 v68, v68, v69, s[40:41]
	v_rsq_f32_e32 v68, v68
	s_nop 0
	v_mul_f32_e32 v69, 0x45800000, v68
	v_cndmask_b32_e64 v70, v68, v69, s[40:41]
	v_pk_mul_f32 v[48:49], v[48:49], v[70:71] op_sel_hi:[1,0]
	v_mad_i64_i32 v[68:69], s[0:1], v66, s56, v[64:65]
	v_mul_f32_e32 v71, 0xbfb8aa3b, v48
	v_exp_f32_e32 v71, v71
	s_nop 0
	v_add_f32_e32 v71, 1.0, v71
	v_rcp_f32_e32 v72, v71
	v_pk_mul_f32 v[32:33], v[32:33], v[70:71] op_sel_hi:[1,0]
	v_mul_f32_e32 v71, 0xbfb8aa3b, v49
	v_exp_f32_e32 v71, v71
	s_nop 0
	v_add_f32_e32 v71, 1.0, v71
	v_rcp_f32_e32 v73, v71
	v_pk_mul_f32 v[34:35], v[34:35], v[70:71] op_sel_hi:[1,0]
	v_pk_mul_f32 v[36:37], v[36:37], v[70:71] op_sel_hi:[1,0]
	v_pk_mul_f32 v[38:39], v[38:39], v[70:71] op_sel_hi:[1,0]
	v_pk_mul_f32 v[48:49], v[48:49], v[72:73]
	s_nop 0
	v_pk_mul_f32 v[32:33], v[32:33], v[48:49]
	v_pk_mul_f32 v[48:49], v[50:51], v[70:71] op_sel_hi:[1,0]
	v_cvt_pk_bf16_f32 v32, v32, v33
	v_mul_f32_e32 v50, 0xbfb8aa3b, v48
	v_mul_f32_e32 v51, 0xbfb8aa3b, v49
	v_exp_f32_e32 v50, v50
	v_exp_f32_e32 v51, v51
	v_add_f32_e32 v50, 1.0, v50
	v_add_f32_e32 v51, 1.0, v51
	v_rcp_f32_e32 v50, v50
	v_rcp_f32_e32 v51, v51
	s_nop 0
	v_pk_mul_f32 v[48:49], v[48:49], v[50:51]
	s_nop 0
	v_pk_mul_f32 v[34:35], v[34:35], v[48:49]
	s_nop 0
	v_cvt_pk_bf16_f32 v33, v34, v35
	v_mov_b32_e32 v222, v32
	v_mov_b32_e32 v223, v33
	v_pk_mul_f32 v[32:33], v[52:53], v[70:71] op_sel_hi:[1,0]
	s_nop 0
	v_mul_f32_e32 v34, 0xbfb8aa3b, v32
	v_mul_f32_e32 v35, 0xbfb8aa3b, v33
	v_exp_f32_e32 v34, v34
	v_exp_f32_e32 v35, v35
	v_add_f32_e32 v34, 1.0, v34
	v_add_f32_e32 v35, 1.0, v35
	v_rcp_f32_e32 v34, v34
	v_rcp_f32_e32 v35, v35
	s_nop 0
	v_pk_mul_f32 v[32:33], v[32:33], v[34:35]
	v_pk_mul_f32 v[34:35], v[54:55], v[70:71] op_sel_hi:[1,0]
	v_pk_mul_f32 v[32:33], v[36:37], v[32:33]
	v_mul_f32_e32 v36, 0xbfb8aa3b, v34
	v_mul_f32_e32 v37, 0xbfb8aa3b, v35
	v_exp_f32_e32 v36, v36
	v_exp_f32_e32 v37, v37
	v_cvt_pk_bf16_f32 v32, v32, v33
	v_add_f32_e32 v36, 1.0, v36
	v_add_f32_e32 v37, 1.0, v37
	v_rcp_f32_e32 v36, v36
	v_rcp_f32_e32 v37, v37
	s_nop 0
	v_pk_mul_f32 v[34:35], v[34:35], v[36:37]
	s_nop 0
	v_pk_mul_f32 v[34:35], v[38:39], v[34:35]
	v_pk_mul_f32 v[36:37], v[40:41], v[70:71] op_sel_hi:[1,0]
	v_cvt_pk_bf16_f32 v33, v34, v35
	v_mov_b32_e32 v224, v32
	v_mov_b32_e32 v225, v33
	v_lshrrev_b32_e32 v238, 2, v204
	v_and_b32_e32 v238, 8, v238
	v_mov_b32_e32 v239, 0
	v_lshl_add_u64 v[240:241], v[68:69], 0, v[238:239]
	v_permlane32_swap_b32_e32 v222, v224
	v_permlane32_swap_b32_e32 v223, v225
	global_store_dwordx4 v[240:241], v[222:225], off
	v_pk_mul_f32 v[32:33], v[56:57], v[70:71] op_sel_hi:[1,0]
	v_pk_mul_f32 v[38:39], v[42:43], v[70:71] op_sel_hi:[1,0]
	v_mul_f32_e32 v34, 0xbfb8aa3b, v32
	v_mul_f32_e32 v35, 0xbfb8aa3b, v33
	v_exp_f32_e32 v34, v34
	v_exp_f32_e32 v35, v35
	v_add_f32_e32 v34, 1.0, v34
	v_add_f32_e32 v35, 1.0, v35
	v_rcp_f32_e32 v34, v34
	v_rcp_f32_e32 v35, v35
	s_nop 0
	v_pk_mul_f32 v[32:33], v[32:33], v[34:35]
	v_pk_mul_f32 v[34:35], v[58:59], v[70:71] op_sel_hi:[1,0]
	v_pk_mul_f32 v[32:33], v[36:37], v[32:33]
	v_mul_f32_e32 v36, 0xbfb8aa3b, v34
	v_mul_f32_e32 v37, 0xbfb8aa3b, v35
	v_exp_f32_e32 v36, v36
	v_exp_f32_e32 v37, v37
	v_cvt_pk_bf16_f32 v32, v32, v33
	v_add_f32_e32 v36, 1.0, v36
	v_add_f32_e32 v37, 1.0, v37
	v_rcp_f32_e32 v36, v36
	v_rcp_f32_e32 v37, v37
	s_nop 0
	v_pk_mul_f32 v[34:35], v[34:35], v[36:37]
	s_nop 0
	v_pk_mul_f32 v[34:35], v[38:39], v[34:35]
	v_pk_mul_f32 v[36:37], v[44:45], v[70:71] op_sel_hi:[1,0]
	v_cvt_pk_bf16_f32 v33, v34, v35
	v_mov_b32_e32 v226, v32
	v_mov_b32_e32 v227, v33
	v_pk_mul_f32 v[32:33], v[60:61], v[70:71] op_sel_hi:[1,0]
	v_pk_mul_f32 v[38:39], v[46:47], v[70:71] op_sel_hi:[1,0]
	v_mul_f32_e32 v34, 0xbfb8aa3b, v32
	v_mul_f32_e32 v35, 0xbfb8aa3b, v33
	v_exp_f32_e32 v34, v34
	v_exp_f32_e32 v35, v35
	v_add_f32_e32 v34, 1.0, v34
	v_add_f32_e32 v35, 1.0, v35
	v_rcp_f32_e32 v34, v34
	v_rcp_f32_e32 v35, v35
	s_nop 0
	v_pk_mul_f32 v[32:33], v[32:33], v[34:35]
	v_pk_mul_f32 v[34:35], v[62:63], v[70:71] op_sel_hi:[1,0]
	v_pk_mul_f32 v[32:33], v[36:37], v[32:33]
	v_mul_f32_e32 v36, 0xbfb8aa3b, v34
	v_mul_f32_e32 v37, 0xbfb8aa3b, v35
	v_exp_f32_e32 v36, v36
	v_exp_f32_e32 v37, v37
	v_cvt_pk_bf16_f32 v32, v32, v33
	v_add_f32_e32 v36, 1.0, v36
	v_add_f32_e32 v37, 1.0, v37
	v_rcp_f32_e32 v36, v36
	v_rcp_f32_e32 v37, v37
	s_nop 0
	v_pk_mul_f32 v[34:35], v[34:35], v[36:37]
	s_nop 0
	v_pk_mul_f32 v[34:35], v[38:39], v[34:35]
	s_nop 0
	v_cvt_pk_bf16_f32 v33, v34, v35
	v_mov_b32_e32 v228, v32
	v_mov_b32_e32 v229, v33
	s_nop 1
	v_permlane32_swap_b32_e32 v226, v228
	v_permlane32_swap_b32_e32 v227, v229
	global_store_dwordx4 v[240:241], v[226:229], off offset:32
; __device__ __forceinline__ float sigm(float x) { return __builtin_amdgcn_rcpf(1.f + __builtin_amdgcn_exp2f(-LOG2E * x)); }
; __device__ __forceinline__ void epi_swiglu(const f32x16 (&acc)[2][2], int nbase, int tbase, int M, const float* ss, u16* ACT) {
;     ...
;     const int tok = tbase + tb * 32 + l32;
;     if (tok < M) {
;       const float rs = rsqrtf(ss[tok] * (1.f / 1024.f) + EPSN);
;       u16* dst = ACT + (size_t)tok * FFD + cb + 4 * h;
; #pragma unroll
;       for (int i = 0; i < 4; ++i) {
;         float o[4];
; #pragma unroll
;         for (int j = 0; j < 4; ++j) {
;           const float g = acc[0][tb][4 * i + j] * rs, u = acc[1][tb][4 * i + j] * rs;
;           o[j] = g * sigm(g) * u;
;         }
;         *(u32x2*)(dst + 8 * i) = (u32x2){pk_bf16(o[0], o[1]), pk_bf16(o[2], o[3])};
;       }
.LBB0_99:
	s_or_b64 exec, exec, s[34:35]
	v_or_b32_e32 v32, 32, v66
	v_cmp_gt_i32_e64 s[40:41], s62, v32
	s_and_saveexec_b64 s[34:35], s[40:41]
	s_cbranch_execz .LBB0_84
	v_lshl_add_u64 v[34:35], v[66:67], 2, s[44:45]
	v_mov_b32_e32 v33, v245
	v_fmamk_f32 v33, v33, 0x3a800000, v205
	v_cmp_gt_f32_e64 s[40:41], s21, v33
	v_mul_f32_e32 v34, 0x4b800000, v33
	s_nop 0
	v_cndmask_b32_e64 v33, v33, v34, s[40:41]
	v_rsq_f32_e32 v33, v33
	s_nop 0
	v_mul_f32_e32 v34, 0x45800000, v33
	v_cndmask_b32_e64 v34, v33, v34, s[40:41]
	v_pk_mul_f32 v[16:17], v[16:17], v[34:35] op_sel_hi:[1,0]
	v_mad_i64_i32 v[32:33], s[0:1], v32, s56, v[64:65]
	v_mul_f32_e32 v35, 0xbfb8aa3b, v16
	v_exp_f32_e32 v35, v35
	s_nop 0
	v_add_f32_e32 v35, 1.0, v35
	v_rcp_f32_e32 v36, v35
	v_pk_mul_f32 v[0:1], v[0:1], v[34:35] op_sel_hi:[1,0]
	v_mul_f32_e32 v35, 0xbfb8aa3b, v17
	v_exp_f32_e32 v35, v35
	s_nop 0
	v_add_f32_e32 v35, 1.0, v35
	v_rcp_f32_e32 v37, v35
	v_pk_mul_f32 v[2:3], v[2:3], v[34:35] op_sel_hi:[1,0]
	v_pk_mul_f32 v[4:5], v[4:5], v[34:35] op_sel_hi:[1,0]
	v_pk_mul_f32 v[6:7], v[6:7], v[34:35] op_sel_hi:[1,0]
	v_pk_mul_f32 v[16:17], v[16:17], v[36:37]
	s_nop 0
	v_pk_mul_f32 v[0:1], v[0:1], v[16:17]
	v_pk_mul_f32 v[16:17], v[18:19], v[34:35] op_sel_hi:[1,0]
	v_cvt_pk_bf16_f32 v0, v0, v1
	v_mul_f32_e32 v18, 0xbfb8aa3b, v16
	v_mul_f32_e32 v19, 0xbfb8aa3b, v17
	v_exp_f32_e32 v18, v18
	v_exp_f32_e32 v19, v19
	v_add_f32_e32 v18, 1.0, v18
	v_add_f32_e32 v19, 1.0, v19
	v_rcp_f32_e32 v18, v18
	v_rcp_f32_e32 v19, v19
	s_nop 0
	v_pk_mul_f32 v[16:17], v[16:17], v[18:19]
	s_nop 0
	v_pk_mul_f32 v[2:3], v[2:3], v[16:17]
	s_nop 0
	v_cvt_pk_bf16_f32 v1, v2, v3
	v_mov_b32_e32 v230, v0
	v_mov_b32_e32 v231, v1
	v_pk_mul_f32 v[0:1], v[20:21], v[34:35] op_sel_hi:[1,0]
	s_nop 0
	v_mul_f32_e32 v2, 0xbfb8aa3b, v0
	v_mul_f32_e32 v3, 0xbfb8aa3b, v1
	v_exp_f32_e32 v2, v2
	v_exp_f32_e32 v3, v3
	v_add_f32_e32 v2, 1.0, v2
	v_add_f32_e32 v3, 1.0, v3
	v_rcp_f32_e32 v2, v2
	v_rcp_f32_e32 v3, v3
	s_nop 0
	v_pk_mul_f32 v[0:1], v[0:1], v[2:3]
	v_pk_mul_f32 v[2:3], v[22:23], v[34:35] op_sel_hi:[1,0]
	v_pk_mul_f32 v[0:1], v[4:5], v[0:1]
	v_mul_f32_e32 v4, 0xbfb8aa3b, v2
	v_mul_f32_e32 v5, 0xbfb8aa3b, v3
	v_exp_f32_e32 v4, v4
	v_exp_f32_e32 v5, v5
	v_cvt_pk_bf16_f32 v0, v0, v1
	v_add_f32_e32 v4, 1.0, v4
	v_add_f32_e32 v5, 1.0, v5
	v_rcp_f32_e32 v4, v4
	v_rcp_f32_e32 v5, v5
	s_nop 0
	v_pk_mul_f32 v[2:3], v[2:3], v[4:5]
	s_nop 0
	v_pk_mul_f32 v[2:3], v[6:7], v[2:3]
	v_pk_mul_f32 v[4:5], v[8:9], v[34:35] op_sel_hi:[1,0]
	v_cvt_pk_bf16_f32 v1, v2, v3
	v_mov_b32_e32 v232, v0
	v_mov_b32_e32 v233, v1
	v_lshrrev_b32_e32 v238, 2, v204
	v_and_b32_e32 v238, 8, v238
	v_mov_b32_e32 v239, 0
	v_lshl_add_u64 v[240:241], v[32:33], 0, v[238:239]
	v_permlane32_swap_b32_e32 v230, v232
	v_permlane32_swap_b32_e32 v231, v233
	global_store_dwordx4 v[240:241], v[230:233], off
	v_pk_mul_f32 v[0:1], v[24:25], v[34:35] op_sel_hi:[1,0]
	v_pk_mul_f32 v[6:7], v[10:11], v[34:35] op_sel_hi:[1,0]
	v_mul_f32_e32 v2, 0xbfb8aa3b, v0
	v_mul_f32_e32 v3, 0xbfb8aa3b, v1
	v_exp_f32_e32 v2, v2
	v_exp_f32_e32 v3, v3
	v_add_f32_e32 v2, 1.0, v2
	v_add_f32_e32 v3, 1.0, v3
	v_rcp_f32_e32 v2, v2
	v_rcp_f32_e32 v3, v3
	s_nop 0
	v_pk_mul_f32 v[0:1], v[0:1], v[2:3]
	v_pk_mul_f32 v[2:3], v[26:27], v[34:35] op_sel_hi:[1,0]
	v_pk_mul_f32 v[0:1], v[4:5], v[0:1]
	v_mul_f32_e32 v4, 0xbfb8aa3b, v2
	v_mul_f32_e32 v5, 0xbfb8aa3b, v3
	v_exp_f32_e32 v4, v4
	v_exp_f32_e32 v5, v5
	v_cvt_pk_bf16_f32 v0, v0, v1
	v_add_f32_e32 v4, 1.0, v4
	v_add_f32_e32 v5, 1.0, v5
	v_rcp_f32_e32 v4, v4
	v_rcp_f32_e32 v5, v5
	s_nop 0
	v_pk_mul_f32 v[2:3], v[2:3], v[4:5]
	s_nop 0
	v_pk_mul_f32 v[2:3], v[6:7], v[2:3]
	v_pk_mul_f32 v[4:5], v[12:13], v[34:35] op_sel_hi:[1,0]
	v_cvt_pk_bf16_f32 v1, v2, v3
	v_mov_b32_e32 v234, v0
	v_mov_b32_e32 v235, v1
	v_pk_mul_f32 v[0:1], v[28:29], v[34:35] op_sel_hi:[1,0]
	v_pk_mul_f32 v[6:7], v[14:15], v[34:35] op_sel_hi:[1,0]
	v_mul_f32_e32 v2, 0xbfb8aa3b, v0
	v_mul_f32_e32 v3, 0xbfb8aa3b, v1
	v_exp_f32_e32 v2, v2
	v_exp_f32_e32 v3, v3
	v_add_f32_e32 v2, 1.0, v2
	v_add_f32_e32 v3, 1.0, v3
	v_rcp_f32_e32 v2, v2
	v_rcp_f32_e32 v3, v3
	s_nop 0
	v_pk_mul_f32 v[0:1], v[0:1], v[2:3]
	v_pk_mul_f32 v[2:3], v[30:31], v[34:35] op_sel_hi:[1,0]
	v_pk_mul_f32 v[0:1], v[4:5], v[0:1]
	v_mul_f32_e32 v4, 0xbfb8aa3b, v2
	v_mul_f32_e32 v5, 0xbfb8aa3b, v3
	v_exp_f32_e32 v4, v4
	v_exp_f32_e32 v5, v5
	v_cvt_pk_bf16_f32 v0, v0, v1
	v_add_f32_e32 v4, 1.0, v4
	v_add_f32_e32 v5, 1.0, v5
	v_rcp_f32_e32 v4, v4
	v_rcp_f32_e32 v5, v5
	s_nop 0
	v_pk_mul_f32 v[2:3], v[2:3], v[4:5]
	s_nop 0
	v_pk_mul_f32 v[2:3], v[6:7], v[2:3]
	s_nop 0
	v_cvt_pk_bf16_f32 v1, v2, v3
	v_mov_b32_e32 v236, v0
	v_mov_b32_e32 v237, v1
	s_nop 1
	v_permlane32_swap_b32_e32 v234, v236
	v_permlane32_swap_b32_e32 v235, v237
	global_store_dwordx4 v[240:241], v[234:237], off offset:32
	s_branch .LBB0_84
